# attention MFMAs switched to the non-scaled v_mfma_f32_32x32x64_f8f6f4 encoding (same fp8 math, unit scale); DMA and LDS reads interleaved between MFMAs
# speedup vs baseline: 1.0191x; 1.0191x over previous
.Latt_pro_done:
	v_mov_b32_e32 v64, 0
	v_mov_b32_e32 v65, 0
	v_mov_b32_e32 v66, 0
	v_mov_b32_e32 v67, 0
	v_mov_b32_e32 v68, 0
	v_mov_b32_e32 v69, 0
	v_mov_b32_e32 v70, 0
	v_mov_b32_e32 v71, 0
	v_mov_b32_e32 v72, 0
	v_mov_b32_e32 v73, 0
	v_mov_b32_e32 v74, 0
	v_mov_b32_e32 v75, 0
	v_mov_b32_e32 v76, 0
	v_mov_b32_e32 v77, 0
	v_mov_b32_e32 v78, 0
	v_mov_b32_e32 v79, 0
	v_mov_b32_e32 v80, 0
	v_mov_b32_e32 v81, 0
	v_mov_b32_e32 v82, 0
	v_mov_b32_e32 v83, 0
	v_mov_b32_e32 v84, 0
	v_mov_b32_e32 v85, 0
	v_mov_b32_e32 v86, 0
	v_mov_b32_e32 v87, 0
	v_mov_b32_e32 v88, 0
	v_mov_b32_e32 v89, 0
	v_mov_b32_e32 v90, 0
	v_mov_b32_e32 v91, 0
	v_mov_b32_e32 v92, 0
	v_mov_b32_e32 v93, 0
	v_mov_b32_e32 v94, 0
	v_mov_b32_e32 v95, 0
	v_mov_b32_e32 v96, 0
	v_mov_b32_e32 v97, 0
	v_mov_b32_e32 v98, 0
	v_mov_b32_e32 v99, 0
	v_mov_b32_e32 v100, 0
	v_mov_b32_e32 v101, 0
	v_mov_b32_e32 v102, 0
	v_mov_b32_e32 v103, 0
	v_mov_b32_e32 v104, 0
	v_mov_b32_e32 v105, 0
	v_mov_b32_e32 v106, 0
	v_mov_b32_e32 v107, 0
	v_mov_b32_e32 v108, 0
	v_mov_b32_e32 v109, 0
	v_mov_b32_e32 v110, 0
	v_mov_b32_e32 v111, 0
	v_mov_b32_e32 v112, 0
	v_mov_b32_e32 v113, 0
	v_mov_b32_e32 v114, 0
	v_mov_b32_e32 v115, 0
	v_mov_b32_e32 v116, 0
	v_mov_b32_e32 v117, 0
	v_mov_b32_e32 v118, 0
	v_mov_b32_e32 v119, 0
	v_mov_b32_e32 v120, 0
	v_mov_b32_e32 v121, 0
	v_mov_b32_e32 v122, 0
	v_mov_b32_e32 v123, 0
	v_mov_b32_e32 v124, 0
	v_mov_b32_e32 v125, 0
	v_mov_b32_e32 v126, 0
	v_mov_b32_e32 v127, 0
	v_mov_b32_e32 v16, 0
	v_mov_b32_e32 v17, 0
	v_mov_b32_e32 v18, 0
	v_mov_b32_e32 v19, 0
	v_mov_b32_e32 v20, 0
	v_mov_b32_e32 v21, 0
	v_mov_b32_e32 v22, 0
	v_mov_b32_e32 v23, 0
	v_mov_b32_e32 v24, 0
	v_mov_b32_e32 v25, 0
	v_mov_b32_e32 v26, 0
	v_mov_b32_e32 v27, 0
	v_mov_b32_e32 v28, 0
	v_mov_b32_e32 v29, 0
	v_mov_b32_e32 v30, 0
	v_mov_b32_e32 v31, 0
	v_mov_b32_e32 v11, 0
	s_mov_b32 s16, 0xbf800000
	s_mov_b32 s17, 0xff800000
	s_mov_b32 s13, 0
	s_waitcnt vmcnt(0)
	s_cmp_lt_u32 s18, 4
	s_cbranch_scc0 .Latt_b_entry
	v_mov_b32_e32 v200, 0
	v_mov_b32_e32 v201, 0
	v_mov_b32_e32 v202, 0
	v_mov_b32_e32 v203, 0
	v_mov_b32_e32 v204, 0
	v_mov_b32_e32 v205, 0
	v_mov_b32_e32 v206, 0
	v_mov_b32_e32 v207, 0
	v_mov_b32_e32 v208, 0
	v_mov_b32_e32 v209, 0
	v_mov_b32_e32 v210, 0
	v_mov_b32_e32 v211, 0
	v_mov_b32_e32 v212, 0
	v_mov_b32_e32 v213, 0
	v_mov_b32_e32 v214, 0
	v_mov_b32_e32 v215, 0
	v_mov_b32_e32 v216, 0
	v_mov_b32_e32 v217, 0
	v_mov_b32_e32 v218, 0
	v_mov_b32_e32 v219, 0
	v_mov_b32_e32 v220, 0
	v_mov_b32_e32 v221, 0
	v_mov_b32_e32 v222, 0
	v_mov_b32_e32 v223, 0
	v_mov_b32_e32 v224, 0
	v_mov_b32_e32 v225, 0
	v_mov_b32_e32 v226, 0
	v_mov_b32_e32 v227, 0
	v_mov_b32_e32 v228, 0
	v_mov_b32_e32 v229, 0
	v_mov_b32_e32 v230, 0
	v_mov_b32_e32 v231, 0
	v_mov_b32_e32 v232, 0
	v_mov_b32_e32 v233, 0
	v_mov_b32_e32 v234, 0
	v_mov_b32_e32 v235, 0
	v_mov_b32_e32 v236, 0
	v_mov_b32_e32 v237, 0
	v_mov_b32_e32 v238, 0
	v_mov_b32_e32 v239, 0

.Latt_a_w:
	s_waitcnt vmcnt(3) lgkmcnt(0)
	s_barrier
	s_and_b32 s19, s13, 3
	s_mul_i32 s20, s19, 0x3000
	s_lshl_b32 s21, s19, 13
	s_add_u32 s19, s13, 2
	s_and_b32 s19, s19, 3
	s_mul_i32 s23, s19, 0x3000
	s_add_i32 s23, s23, s14
	s_lshl_b32 s24, s19, 13
	s_add_i32 s24, s24, s14
	s_add_i32 s24, s24, 0xc000
	v_add_u32_e32 v242, s20, v7
	v_add_u32_e32 v243, s20, v8
	v_mfma_f32_32x32x64_f8f6f4 v[64:79], v[200:207], v[232:239], v[64:79]
	ds_read_b128 v[152:155], v242 offset:0
	ds_read_b128 v[156:159], v243 offset:0
	ds_read_b128 v[176:179], v242 offset:1024
	ds_read_b128 v[180:183], v243 offset:1024
	v_mfma_f32_32x32x64_f8f6f4 v[80:95], v[208:215], v[232:239], v[80:95]
	ds_read_b128 v[160:163], v242 offset:4096
	ds_read_b128 v[164:167], v243 offset:4096
	ds_read_b128 v[184:187], v242 offset:5120
	ds_read_b128 v[188:191], v243 offset:5120
	s_cmp_lt_u32 s13, 126
	s_cbranch_scc0 .Latt_sk0_a
	s_mov_b32 m0, s23
	s_nop 0
	global_load_lds_dwordx4 v4, s[6:7]
.Latt_sk0_a:
	v_mfma_f32_32x32x64_f8f6f4 v[96:111], v[216:223], v[232:239], v[96:111]
	ds_read_b128 v[168:171], v242 offset:8192
	ds_read_b128 v[172:175], v243 offset:8192
	ds_read_b128 v[192:195], v242 offset:9216
	ds_read_b128 v[196:199], v243 offset:9216
	s_cmp_lt_u32 s13, 126
	s_cbranch_scc0 .Latt_sk1_a
	s_add_i32 s23, s23, 0x2000
	s_mov_b32 m0, s23
	s_nop 0
	global_load_lds_dwordx4 v5, s[6:7]
.Latt_sk1_a:
	v_mfma_f32_32x32x64_f8f6f4 v[112:127], v[224:231], v[232:239], v[112:127]
	s_cmp_lt_u32 s13, 126
	s_cbranch_scc0 .Latt_sk2_a
	s_mov_b32 m0, s24
	s_add_u32 s6, s6, 0x3000
	s_addc_u32 s7, s7, 0
	global_load_lds_dwordx4 v6, s[8:9]
	s_add_u32 s8, s8, 64
	s_addc_u32 s9, s9, 0
.Latt_sk2_a:
	v_add_u32_e32 v244, s21, v9
	v_add_u32_e32 v245, s21, v10
	s_waitcnt lgkmcnt(10)
	v_mfma_f32_32x32x64_f8f6f4 v[32:47], v[152:159], v[128:135], v[16:31]
	ds_read_b128 v[200:203], v244 offset:0
	ds_read_b128 v[204:207], v245 offset:0
	s_waitcnt lgkmcnt(10)
	v_mfma_f32_32x32x64_f8f6f4 v[48:63], v[176:183], v[128:135], v[16:31]
	ds_read_b128 v[208:211], v244 offset:2048
	ds_read_b128 v[212:215], v245 offset:2048
	s_waitcnt lgkmcnt(10)
	v_mfma_f32_32x32x64_f8f6f4 v[32:47], v[160:167], v[136:143], v[32:47]
	ds_read_b128 v[216:219], v244 offset:4096
	ds_read_b128 v[220:223], v245 offset:4096
	s_waitcnt lgkmcnt(10)
	v_mfma_f32_32x32x64_f8f6f4 v[48:63], v[184:191], v[136:143], v[48:63]
	ds_read_b128 v[224:227], v244 offset:6144
	ds_read_b128 v[228:231], v245 offset:6144
	s_waitcnt lgkmcnt(10)
	v_mfma_f32_32x32x64_f8f6f4 v[32:47], v[168:175], v[144:151], v[32:47]
	s_waitcnt lgkmcnt(8)
	v_mfma_f32_32x32x64_f8f6f4 v[48:63], v[192:199], v[144:151], v[48:63]
	s_nop 15
	s_nop 3
	v_exp_f32_e32 v32, v32
	v_exp_f32_e32 v33, v33
	v_exp_f32_e32 v34, v34
	v_exp_f32_e32 v35, v35
	v_exp_f32_e32 v36, v36
	v_exp_f32_e32 v37, v37
	v_exp_f32_e32 v38, v38
	v_exp_f32_e32 v39, v39
	v_add_f32_e32 v12, v32, v33
	v_add_f32_e32 v12, v12, v34
	v_add_f32_e32 v12, v12, v35
	v_exp_f32_e32 v40, v40
	v_exp_f32_e32 v41, v41
	v_exp_f32_e32 v42, v42
	v_exp_f32_e32 v43, v43
	v_add_f32_e32 v12, v12, v36
	v_add_f32_e32 v12, v12, v37
	v_add_f32_e32 v12, v12, v38
	v_add_f32_e32 v12, v12, v39
	v_exp_f32_e32 v44, v44
	v_exp_f32_e32 v45, v45
	v_exp_f32_e32 v46, v46
	v_exp_f32_e32 v47, v47
	v_add_f32_e32 v12, v12, v40
	v_add_f32_e32 v12, v12, v41
	v_add_f32_e32 v12, v12, v42
	v_add_f32_e32 v12, v12, v43
	v_exp_f32_e32 v48, v48
	v_exp_f32_e32 v49, v49
	v_exp_f32_e32 v50, v50
	v_exp_f32_e32 v51, v51
	v_add_f32_e32 v12, v12, v44
	v_add_f32_e32 v12, v12, v45
	v_add_f32_e32 v12, v12, v46
	v_add_f32_e32 v12, v12, v47
	v_exp_f32_e32 v52, v52
	v_exp_f32_e32 v53, v53
	v_exp_f32_e32 v54, v54
	v_exp_f32_e32 v55, v55
	v_add_f32_e32 v13, v48, v49
	v_add_f32_e32 v13, v13, v50
	v_add_f32_e32 v13, v13, v51
	v_exp_f32_e32 v56, v56
	v_exp_f32_e32 v57, v57
	v_exp_f32_e32 v58, v58
	v_exp_f32_e32 v59, v59
	v_add_f32_e32 v13, v13, v52
	v_add_f32_e32 v13, v13, v53
	v_add_f32_e32 v13, v13, v54
	v_add_f32_e32 v13, v13, v55
	v_exp_f32_e32 v60, v60
	v_exp_f32_e32 v61, v61
	v_exp_f32_e32 v62, v62
	v_exp_f32_e32 v63, v63
	v_add_f32_e32 v13, v13, v56
	v_add_f32_e32 v13, v13, v57
	v_add_f32_e32 v13, v13, v58
	v_add_f32_e32 v13, v13, v59
	v_add_f32_e32 v13, v13, v60
	v_add_f32_e32 v13, v13, v61
	v_add_f32_e32 v13, v13, v62
	v_add_f32_e32 v13, v13, v63
	v_add_f32_e32 v12, v12, v13
	v_mov_b32_e32 v14, v12
	s_nop 1
	v_permlane32_swap_b32_e32 v12, v14
	v_add_f32_e32 v12, v12, v14
	v_cmp_nge_f32_e32 vcc, s16, v12
	s_cbranch_vccnz .Latt_rare_a
	v_add_f32_e32 v11, v11, v12
.Latt_pack_a:
	v_cvt_pk_fp8_f32 v232, v32, v33
	v_cvt_pk_fp8_f32 v233, v36, v37
	v_cvt_pk_fp8_f32 v234, v40, v41
	v_cvt_pk_fp8_f32 v235, v44, v45
	v_cvt_pk_fp8_f32 v236, v48, v49
	v_cvt_pk_fp8_f32 v237, v52, v53
	v_cvt_pk_fp8_f32 v238, v56, v57
	v_cvt_pk_fp8_f32 v239, v60, v61
	v_cvt_pk_fp8_f32 v232, v34, v35 op_sel:[0,0,1]
	v_cvt_pk_fp8_f32 v233, v38, v39 op_sel:[0,0,1]
	v_cvt_pk_fp8_f32 v234, v42, v43 op_sel:[0,0,1]
	v_cvt_pk_fp8_f32 v235, v46, v47 op_sel:[0,0,1]
	v_cvt_pk_fp8_f32 v236, v50, v51 op_sel:[0,0,1]
	v_cvt_pk_fp8_f32 v237, v54, v55 op_sel:[0,0,1]
	v_cvt_pk_fp8_f32 v238, v58, v59 op_sel:[0,0,1]
	v_cvt_pk_fp8_f32 v239, v62, v63 op_sel:[0,0,1]
	s_add_u32 s13, s13, 1
	s_cmp_lt_u32 s13, 128
	s_cbranch_scc1 .Latt_a_loop
	s_waitcnt lgkmcnt(0)
	v_mfma_f32_32x32x64_f8f6f4 v[64:79], v[200:207], v[232:239], v[64:79]
	v_mfma_f32_32x32x64_f8f6f4 v[80:95], v[208:215], v[232:239], v[80:95]
	v_mfma_f32_32x32x64_f8f6f4 v[96:111], v[216:223], v[232:239], v[96:111]
	v_mfma_f32_32x32x64_f8f6f4 v[112:127], v[224:231], v[232:239], v[112:127]
	s_branch .Latt_final

.Latt_b_entry:
	s_setprio 1
	s_waitcnt vmcnt(2) lgkmcnt(0)
	s_barrier
	s_and_b32 s19, s13, 3
	s_mul_i32 s20, s19, 0x3000
	s_add_u32 s19, s13, 3
	s_and_b32 s19, s19, 3
	s_lshl_b32 s21, s19, 13
	s_add_u32 s19, s13, 2
	s_and_b32 s19, s19, 3
	s_mul_i32 s23, s19, 0x3000
	s_add_i32 s23, s23, s14
	s_lshl_b32 s24, s19, 13
	s_add_i32 s24, s24, s14
	s_add_i32 s24, s24, 0xc000
	v_add_u32_e32 v242, s20, v7
	v_add_u32_e32 v243, s20, v8
	ds_read_b128 v[152:155], v242 offset:0
	ds_read_b128 v[156:159], v243 offset:0
	ds_read_b128 v[176:179], v242 offset:1024
	ds_read_b128 v[180:183], v243 offset:1024
	ds_read_b128 v[160:163], v242 offset:4096
	ds_read_b128 v[164:167], v243 offset:4096
	ds_read_b128 v[184:187], v242 offset:5120
	ds_read_b128 v[188:191], v243 offset:5120
	ds_read_b128 v[168:171], v242 offset:8192
	ds_read_b128 v[172:175], v243 offset:8192
	ds_read_b128 v[192:195], v242 offset:9216
	ds_read_b128 v[196:199], v243 offset:9216
	s_cmp_lt_u32 s13, 126
	s_cbranch_scc0 .Latt_sk0_b0
	s_mov_b32 m0, s23
	s_nop 0
	global_load_lds_dwordx4 v4, s[6:7]
.Latt_sk0_b0:
	s_cmp_lt_u32 s13, 126
	s_cbranch_scc0 .Latt_sk2_b0
	s_mov_b32 m0, s24
	s_add_u32 s6, s6, 0x3000
	s_addc_u32 s7, s7, 0
	global_load_lds_dwordx4 v6, s[8:9]
	s_add_u32 s8, s8, 64
	s_addc_u32 s9, s9, 0
.Latt_sk2_b0:
	s_waitcnt lgkmcnt(10)
	v_mfma_f32_32x32x64_f8f6f4 v[32:47], v[152:159], v[128:135], v[16:31]
	s_waitcnt lgkmcnt(8)
	v_mfma_f32_32x32x64_f8f6f4 v[48:63], v[176:183], v[128:135], v[16:31]
	s_waitcnt lgkmcnt(6)
	v_mfma_f32_32x32x64_f8f6f4 v[32:47], v[160:167], v[136:143], v[32:47]
	s_waitcnt lgkmcnt(4)
	v_mfma_f32_32x32x64_f8f6f4 v[48:63], v[184:191], v[136:143], v[48:63]
	s_waitcnt lgkmcnt(2)
	v_mfma_f32_32x32x64_f8f6f4 v[32:47], v[168:175], v[144:151], v[32:47]
	s_waitcnt lgkmcnt(0)
	v_mfma_f32_32x32x64_f8f6f4 v[48:63], v[192:199], v[144:151], v[48:63]
	s_mov_b32 s13, 1

.Latt_b_w:
	s_waitcnt vmcnt(2) lgkmcnt(0)
	s_barrier
	s_and_b32 s19, s13, 3
	s_mul_i32 s20, s19, 0x3000
	s_add_u32 s19, s13, 3
	s_and_b32 s19, s19, 3
	s_lshl_b32 s21, s19, 13
	s_add_u32 s19, s13, 2
	s_and_b32 s19, s19, 3
	s_mul_i32 s23, s19, 0x3000
	s_add_i32 s23, s23, s14
	s_lshl_b32 s24, s19, 13
	s_add_i32 s24, s24, s14
	s_add_i32 s24, s24, 0xc000
	v_add_u32_e32 v244, s21, v9
	v_add_u32_e32 v245, s21, v10
	ds_read_b128 v[200:203], v244 offset:0
	ds_read_b128 v[204:207], v245 offset:0
	ds_read_b128 v[208:211], v244 offset:2048
	ds_read_b128 v[212:215], v245 offset:2048
	ds_read_b128 v[216:219], v244 offset:4096
	ds_read_b128 v[220:223], v245 offset:4096
	ds_read_b128 v[224:227], v244 offset:6144
	ds_read_b128 v[228:231], v245 offset:6144
	v_add_u32_e32 v242, s20, v7
	v_add_u32_e32 v243, s20, v8
	v_exp_f32_e32 v32, v32
	v_exp_f32_e32 v33, v33
	v_exp_f32_e32 v34, v34
	v_exp_f32_e32 v35, v35
	v_exp_f32_e32 v36, v36
	v_exp_f32_e32 v37, v37
	v_exp_f32_e32 v38, v38
	v_exp_f32_e32 v39, v39
	v_add_f32_e32 v12, v32, v33
	v_add_f32_e32 v12, v12, v34
	v_add_f32_e32 v12, v12, v35
	v_exp_f32_e32 v40, v40
	v_exp_f32_e32 v41, v41
	v_exp_f32_e32 v42, v42
	v_exp_f32_e32 v43, v43
	v_add_f32_e32 v12, v12, v36
	v_add_f32_e32 v12, v12, v37
	v_add_f32_e32 v12, v12, v38
	v_add_f32_e32 v12, v12, v39
	v_exp_f32_e32 v44, v44
	v_exp_f32_e32 v45, v45
	v_exp_f32_e32 v46, v46
	v_exp_f32_e32 v47, v47
	v_add_f32_e32 v12, v12, v40
	v_add_f32_e32 v12, v12, v41
	v_add_f32_e32 v12, v12, v42
	v_add_f32_e32 v12, v12, v43
	v_exp_f32_e32 v48, v48
	v_exp_f32_e32 v49, v49
	v_exp_f32_e32 v50, v50
	v_exp_f32_e32 v51, v51
	v_add_f32_e32 v12, v12, v44
	v_add_f32_e32 v12, v12, v45
	v_add_f32_e32 v12, v12, v46
	v_add_f32_e32 v12, v12, v47
	v_exp_f32_e32 v52, v52
	v_exp_f32_e32 v53, v53
	v_exp_f32_e32 v54, v54
	v_exp_f32_e32 v55, v55
	v_add_f32_e32 v13, v48, v49
	v_add_f32_e32 v13, v13, v50
	v_add_f32_e32 v13, v13, v51
	v_exp_f32_e32 v56, v56
	v_exp_f32_e32 v57, v57
	v_exp_f32_e32 v58, v58
	v_exp_f32_e32 v59, v59
	v_add_f32_e32 v13, v13, v52
	v_add_f32_e32 v13, v13, v53
	v_add_f32_e32 v13, v13, v54
	v_add_f32_e32 v13, v13, v55
	v_exp_f32_e32 v60, v60
	v_exp_f32_e32 v61, v61
	v_exp_f32_e32 v62, v62
	v_exp_f32_e32 v63, v63
	v_add_f32_e32 v13, v13, v56
	v_add_f32_e32 v13, v13, v57
	v_add_f32_e32 v13, v13, v58
	v_add_f32_e32 v13, v13, v59
	v_add_f32_e32 v13, v13, v60
	v_add_f32_e32 v13, v13, v61
	v_add_f32_e32 v13, v13, v62
	v_add_f32_e32 v13, v13, v63
	v_add_f32_e32 v12, v12, v13
	v_mov_b32_e32 v14, v12
	s_nop 1
	v_permlane32_swap_b32_e32 v12, v14
	v_add_f32_e32 v12, v12, v14
	v_cmp_nge_f32_e32 vcc, s16, v12
	s_cbranch_vccnz .Latt_rare_b
	v_add_f32_e32 v11, v11, v12
.Latt_pack_b:
	v_cvt_pk_fp8_f32 v232, v32, v33
	v_cvt_pk_fp8_f32 v233, v36, v37
	v_cvt_pk_fp8_f32 v234, v40, v41
	v_cvt_pk_fp8_f32 v235, v44, v45
	v_cvt_pk_fp8_f32 v236, v48, v49
	v_cvt_pk_fp8_f32 v237, v52, v53
	v_cvt_pk_fp8_f32 v238, v56, v57
	v_cvt_pk_fp8_f32 v239, v60, v61
	v_cvt_pk_fp8_f32 v232, v34, v35 op_sel:[0,0,1]
	v_cvt_pk_fp8_f32 v233, v38, v39 op_sel:[0,0,1]
	v_cvt_pk_fp8_f32 v234, v42, v43 op_sel:[0,0,1]
	v_cvt_pk_fp8_f32 v235, v46, v47 op_sel:[0,0,1]
	v_cvt_pk_fp8_f32 v236, v50, v51 op_sel:[0,0,1]
	v_cvt_pk_fp8_f32 v237, v54, v55 op_sel:[0,0,1]
	v_cvt_pk_fp8_f32 v238, v58, v59 op_sel:[0,0,1]
	v_cvt_pk_fp8_f32 v239, v62, v63 op_sel:[0,0,1]
	s_waitcnt lgkmcnt(6)
	s_nop 0
	v_mfma_f32_32x32x64_f8f6f4 v[64:79], v[200:207], v[232:239], v[64:79]
	ds_read_b128 v[152:155], v242 offset:0
	ds_read_b128 v[156:159], v243 offset:0
	ds_read_b128 v[176:179], v242 offset:1024
	ds_read_b128 v[180:183], v243 offset:1024
	s_waitcnt lgkmcnt(8)
	v_mfma_f32_32x32x64_f8f6f4 v[80:95], v[208:215], v[232:239], v[80:95]
	ds_read_b128 v[160:163], v242 offset:4096
	ds_read_b128 v[164:167], v243 offset:4096
	ds_read_b128 v[184:187], v242 offset:5120
	ds_read_b128 v[188:191], v243 offset:5120
	s_cmp_lt_u32 s13, 126
	s_cbranch_scc0 .Latt_sk0_b
	s_mov_b32 m0, s23
	s_nop 0
	global_load_lds_dwordx4 v4, s[6:7]
.Latt_sk0_b:
	s_waitcnt lgkmcnt(10)
	v_mfma_f32_32x32x64_f8f6f4 v[96:111], v[216:223], v[232:239], v[96:111]
	ds_read_b128 v[168:171], v242 offset:8192
	ds_read_b128 v[172:175], v243 offset:8192
	ds_read_b128 v[192:195], v242 offset:9216
	ds_read_b128 v[196:199], v243 offset:9216
	s_cmp_lt_u32 s13, 126
	s_cbranch_scc0 .Latt_sk2_b
	s_mov_b32 m0, s24
	s_add_u32 s6, s6, 0x3000
	s_addc_u32 s7, s7, 0
	global_load_lds_dwordx4 v6, s[8:9]
	s_add_u32 s8, s8, 64
	s_addc_u32 s9, s9, 0
.Latt_sk2_b:
	s_waitcnt lgkmcnt(12)
	v_mfma_f32_32x32x64_f8f6f4 v[112:127], v[224:231], v[232:239], v[112:127]
	s_waitcnt lgkmcnt(10)
	v_mfma_f32_32x32x64_f8f6f4 v[32:47], v[152:159], v[128:135], v[16:31]
	s_waitcnt lgkmcnt(8)
	v_mfma_f32_32x32x64_f8f6f4 v[48:63], v[176:183], v[128:135], v[16:31]
	s_waitcnt lgkmcnt(6)
	v_mfma_f32_32x32x64_f8f6f4 v[32:47], v[160:167], v[136:143], v[32:47]
	s_waitcnt lgkmcnt(4)
	v_mfma_f32_32x32x64_f8f6f4 v[48:63], v[184:191], v[136:143], v[48:63]
	s_waitcnt lgkmcnt(2)
	v_mfma_f32_32x32x64_f8f6f4 v[32:47], v[168:175], v[144:151], v[32:47]
	s_waitcnt lgkmcnt(0)
	v_mfma_f32_32x32x64_f8f6f4 v[48:63], v[192:199], v[144:151], v[48:63]
	s_add_u32 s13, s13, 1
	s_cmp_lt_u32 s13, 128
	s_cbranch_scc1 .Latt_b_loop
	s_mov_b32 s19, 3
	s_lshl_b32 s21, s19, 13
	v_add_u32_e32 v244, s21, v9
	v_add_u32_e32 v245, s21, v10
	ds_read_b128 v[200:203], v244 offset:0
	ds_read_b128 v[204:207], v245 offset:0
	ds_read_b128 v[208:211], v244 offset:2048
	ds_read_b128 v[212:215], v245 offset:2048
	ds_read_b128 v[216:219], v244 offset:4096
	ds_read_b128 v[220:223], v245 offset:4096
	ds_read_b128 v[224:227], v244 offset:6144
	ds_read_b128 v[228:231], v245 offset:6144
	s_nop 9
	v_exp_f32_e32 v32, v32
	v_exp_f32_e32 v33, v33
	v_exp_f32_e32 v34, v34
	v_exp_f32_e32 v35, v35
	v_exp_f32_e32 v36, v36
	v_exp_f32_e32 v37, v37
	v_exp_f32_e32 v38, v38
	v_exp_f32_e32 v39, v39
	v_add_f32_e32 v12, v32, v33
	v_add_f32_e32 v12, v12, v34
	v_add_f32_e32 v12, v12, v35
	v_exp_f32_e32 v40, v40
	v_exp_f32_e32 v41, v41
	v_exp_f32_e32 v42, v42
	v_exp_f32_e32 v43, v43
	v_add_f32_e32 v12, v12, v36
	v_add_f32_e32 v12, v12, v37
	v_add_f32_e32 v12, v12, v38
	v_add_f32_e32 v12, v12, v39
	v_exp_f32_e32 v44, v44
	v_exp_f32_e32 v45, v45
	v_exp_f32_e32 v46, v46
	v_exp_f32_e32 v47, v47
	v_add_f32_e32 v12, v12, v40
	v_add_f32_e32 v12, v12, v41
	v_add_f32_e32 v12, v12, v42
	v_add_f32_e32 v12, v12, v43
	v_exp_f32_e32 v48, v48
	v_exp_f32_e32 v49, v49
	v_exp_f32_e32 v50, v50
	v_exp_f32_e32 v51, v51
	v_add_f32_e32 v12, v12, v44
	v_add_f32_e32 v12, v12, v45
	v_add_f32_e32 v12, v12, v46
	v_add_f32_e32 v12, v12, v47
	v_exp_f32_e32 v52, v52
	v_exp_f32_e32 v53, v53
	v_exp_f32_e32 v54, v54
	v_exp_f32_e32 v55, v55
	v_add_f32_e32 v13, v48, v49
	v_add_f32_e32 v13, v13, v50
	v_add_f32_e32 v13, v13, v51
	v_exp_f32_e32 v56, v56
	v_exp_f32_e32 v57, v57
	v_exp_f32_e32 v58, v58
	v_exp_f32_e32 v59, v59
	v_add_f32_e32 v13, v13, v52
	v_add_f32_e32 v13, v13, v53
	v_add_f32_e32 v13, v13, v54
	v_add_f32_e32 v13, v13, v55
	v_exp_f32_e32 v60, v60
	v_exp_f32_e32 v61, v61
	v_exp_f32_e32 v62, v62
	v_exp_f32_e32 v63, v63
	v_add_f32_e32 v13, v13, v56
	v_add_f32_e32 v13, v13, v57
	v_add_f32_e32 v13, v13, v58
	v_add_f32_e32 v13, v13, v59
	v_add_f32_e32 v13, v13, v60
	v_add_f32_e32 v13, v13, v61
	v_add_f32_e32 v13, v13, v62
	v_add_f32_e32 v13, v13, v63
	v_add_f32_e32 v12, v12, v13
	v_mov_b32_e32 v14, v12
	s_nop 1
	v_permlane32_swap_b32_e32 v12, v14
	v_add_f32_e32 v12, v12, v14
	v_cmp_nge_f32_e32 vcc, s16, v12
	s_cbranch_vccnz .Latt_rare_bt
	v_add_f32_e32 v11, v11, v12
.Latt_pack_bt:
	v_cvt_pk_fp8_f32 v232, v32, v33
	v_cvt_pk_fp8_f32 v233, v36, v37
	v_cvt_pk_fp8_f32 v234, v40, v41
	v_cvt_pk_fp8_f32 v235, v44, v45
	v_cvt_pk_fp8_f32 v236, v48, v49
	v_cvt_pk_fp8_f32 v237, v52, v53
	v_cvt_pk_fp8_f32 v238, v56, v57
	v_cvt_pk_fp8_f32 v239, v60, v61
	v_cvt_pk_fp8_f32 v232, v34, v35 op_sel:[0,0,1]
	v_cvt_pk_fp8_f32 v233, v38, v39 op_sel:[0,0,1]
	v_cvt_pk_fp8_f32 v234, v42, v43 op_sel:[0,0,1]
	v_cvt_pk_fp8_f32 v235, v46, v47 op_sel:[0,0,1]
	v_cvt_pk_fp8_f32 v236, v50, v51 op_sel:[0,0,1]
	v_cvt_pk_fp8_f32 v237, v54, v55 op_sel:[0,0,1]
	v_cvt_pk_fp8_f32 v238, v58, v59 op_sel:[0,0,1]
	v_cvt_pk_fp8_f32 v239, v62, v63 op_sel:[0,0,1]
	s_waitcnt lgkmcnt(0)
	s_nop 1
	v_mfma_f32_32x32x64_f8f6f4 v[64:79], v[200:207], v[232:239], v[64:79]
	v_mfma_f32_32x32x64_f8f6f4 v[80:95], v[208:215], v[232:239], v[80:95]
	v_mfma_f32_32x32x64_f8f6f4 v[96:111], v[216:223], v[232:239], v[96:111]
	v_mfma_f32_32x32x64_f8f6f4 v[112:127], v[224:231], v[232:239], v[112:127]
	s_setprio 0
	s_branch .Latt_final
